# SB stop-flag tree with three-input AND (v_bitop3 0x80): 4 instead of 7 VALU after the step barrier; on top of hand-over trim
# speedup vs baseline: 1.0027x; 1.0020x over previous
.LBB0_364:
	s_and_b32 s90, s86, 8
	s_xor_b32 s82, s90, 8
	s_lshl_b32 s82, s82, 2
	s_add_i32 s82, s82, 0
	s_add_i32 s82, s82, 0x241c0
	v_mov_b32_e32 v82, s82
	ds_read_b128 v[136:139], v82
	ds_read_b128 v[140:143], v82 offset:16
	s_waitcnt lgkmcnt(0)
	v_bitop3_b32 v136, v136, v137, v138 bitop3:0x80
	v_bitop3_b32 v140, v140, v141, v142 bitop3:0x80
	v_bitop3_b32 v136, v136, v139, v143 bitop3:0x80
	v_and_b32_e32 v82, v136, v140
	v_cmp_ne_u32_e64 s[82:83], 0, v82
	s_and_b64 vcc, exec, s[82:83]
	s_cbranch_vccnz .LBB0_355
	s_cmp_lt_i32 s84, 3
	s_cbranch_scc0 .LBB0_373
	s_andn2_b64 vcc, exec, s[72:73]
	s_cbranch_vccz .LBB0_374
